# context-stream scans paired: one task = both row halves of (b,h,dir), waves 0-3 and 4-7 both compute (two scan waves per SIMD), waves 4-7 also stream the records; half as many scan tasks
# speedup vs baseline: 1.0129x; 1.0129x over previous
.Lsc_task_loop:
	s_cmp_ge_u32 s71, 192
	s_cbranch_scc1 .Lsc_done
	s_cmp_lt_u32 s71, 64
	s_cbranch_scc1 .Lsc_is_sample
	s_sub_u32 s20, s71, 64
	s_lshl_b32 s20, s20, 1
	s_lshr_b32 s21, s20, 2
	s_lshl_b32 s22, s21, 8
	s_mov_b32 s23, 16
	s_branch .Lsc_decoded

.Lsc_nopoll:
	s_barrier
	s_cmp_lt_u32 s71, 64
	s_cbranch_scc0 .Lsc_pair
	s_cmp_ge_u32 s0, 4
	s_cbranch_scc1 .Lsc_loader
	s_and_b32 s22, s20, 1
	s_lshl_b32 s22, s22, 5
	s_lshl_b32 s1, s0, 3
	s_add_u32 s22, s22, s1
	v_and_b32_e32 v116, 15, v0
	v_bfe_u32 v117, v0, 4, 2
	v_lshlrev_b32_e32 v111, 4, v116
	v_add_u32_e32 v118, s22, v117
	v_add_u32_e32 v111, 0xf0, v111
	v_lshlrev_b32_e32 v112, 2, v118
	v_add_u32_e32 v112, 0x2f0, v112
	v_lshlrev_b32_e32 v114, 8, v118
	v_lshl_add_u32 v114, v116, 4, v114
	s_lshr_b32 s1, s21, 2
	s_and_b32 s4, s21, 3
	s_lshl_b32 s1, s1, 1
	s_add_u32 s1, s1, s80
	s_lshl_b32 s1, s1, 1
	s_add_u32 s1, s1, s24
	s_lshl_b32 s1, s1, 2
	s_add_u32 s1, s1, s4
	s_lshl_b32 s1, s1, 14
	s_cmp_lt_u32 s71, 64
	s_cbranch_scc0 .Lsc_ctx_init
	ds_read_b64 v[120:121], v131 offset:32
	s_waitcnt lgkmcnt(0)
	v_readfirstlane_b32 s4, v120
	v_readfirstlane_b32 s5, v121
	s_nop 3
	s_add_u32 s4, s4, s1
	s_addc_u32 s5, s5, 0
	s_nop 3
	global_load_dwordx4 v[2:5], v114, s[4:5]
	global_load_dwordx4 v[6:9], v114, s[4:5] offset:1024
	s_lshl_b32 s6, s21, 2
	s_lshr_b32 s6, s21, 2
	s_lshl_b32 s6, s6, 20
	s_add_u32 s6, s6, 0x400000
	s_branch .Lsc_init_done

.Lsc_ld_loop:
	s_waitcnt vmcnt(12)
	s_barrier
	s_mov_b32 s22, s1
	s_mov_b32 m0, s8
	s_nop 0
	global_load_lds_dwordx4 v2, s[4:5]
	s_add_u32 m0, s8, 0x400
	s_nop 0
	global_load_lds_dwordx4 v3, s[4:5]
	s_add_u32 m0, s8, 0x800
	s_nop 0
	global_load_lds_dwordx4 v4, s[4:5]
	s_add_u32 m0, s8, 0xc00
	s_nop 0
	global_load_lds_dwordx4 v5, s[4:5]
	s_add_u32 m0, s8, 0x1000
	s_nop 0
	global_load_lds_dwordx4 v6, s[4:5]
	s_add_u32 m0, s8, 0x1400
	s_nop 0
	global_load_lds_dwordx4 v7, s[4:5]
	s_cmp_lt_u32 s10, s21
	s_cselect_b32 s1, s6, 0
	s_cselect_b32 s14, s7, 0
	s_cselect_b32 s15, 1, 0
	s_add_u32 s4, s4, s1
	s_addc_u32 s5, s5, s14
	s_add_u32 s10, s10, s15
	s_add_u32 s9, s9, 1
	s_add_u32 s8, s8, 0x6000
	s_cmp_eq_u32 s9, 5
	s_cselect_b32 s1, 0x1e000, 0
	s_cselect_b32 s9, 0, s9
	s_sub_u32 s8, s8, s1
	s_sub_u32 s1, s22, 1
	s_cmp_lg_u32 s1, 0
	s_cbranch_scc1 .Lsc_ld_loop
	s_waitcnt vmcnt(0)
	s_barrier
	s_branch .Lsc_next
.Lsc_pair:
	s_cmp_ge_u32 s0, 4
	s_cbranch_scc1 .Lsc_pairB
	s_and_b32 s22, s20, 1
	s_lshl_b32 s22, s22, 5
	s_lshl_b32 s1, s0, 3
	s_add_u32 s22, s22, s1
	v_and_b32_e32 v116, 15, v0
	v_bfe_u32 v117, v0, 4, 2
	v_lshlrev_b32_e32 v111, 4, v116
	v_add_u32_e32 v118, s22, v117
	v_add_u32_e32 v111, 0xf0, v111
	v_lshlrev_b32_e32 v112, 2, v118
	v_add_u32_e32 v112, 0x2f0, v112
	v_lshlrev_b32_e32 v114, 8, v118
	v_lshl_add_u32 v114, v116, 4, v114
	s_lshr_b32 s1, s21, 2
	s_and_b32 s4, s21, 3
	s_lshl_b32 s1, s1, 1
	s_add_u32 s1, s1, s80
	s_lshl_b32 s1, s1, 1
	s_add_u32 s1, s1, s24
	s_lshl_b32 s1, s1, 2
	s_add_u32 s1, s1, s4
	s_lshl_b32 s1, s1, 14
	s_cmp_lt_u32 s71, 64
	s_cbranch_scc0 .Lsc_ctx_init_pa
	ds_read_b64 v[120:121], v131 offset:32
	s_waitcnt lgkmcnt(0)
	v_readfirstlane_b32 s4, v120
	v_readfirstlane_b32 s5, v121
	s_nop 3
	s_add_u32 s4, s4, s1
	s_addc_u32 s5, s5, 0
	s_nop 3
	global_load_dwordx4 v[2:5], v114, s[4:5]
	global_load_dwordx4 v[6:9], v114, s[4:5] offset:1024
	s_lshl_b32 s6, s21, 2
	s_lshr_b32 s6, s21, 2
	s_lshl_b32 s6, s6, 20
	s_add_u32 s6, s6, 0x400000
	s_branch .Lsc_init_done_pa

.Lsc_pairB:
	s_sub_u32 s11, s0, 4
	s_mul_i32 s6, s22, 0x300
	s_cmp_lt_u32 s11, 2
	s_cbranch_scc1 .Lsc_ld_pb_recs
	v_readlane_b32 s4, v253, 30
	v_readlane_b32 s5, v253, 31
	s_mul_i32 s1, s24, 0x1800000
	s_add_u32 s6, s6, s1
	s_branch .Lsc_ld_pb_base

.Lsc_ld_pb_base:
	s_nop 0
	s_add_u32 s4, s4, s6
	s_addc_u32 s5, s5, 0
	s_cmp_eq_u32 s24, 0
	s_cbranch_scc1 .Lsc_ld_pb_fwd
	s_sub_u32 s1, s23, 1
	s_mul_i32 s1, s1, 0x3000
	s_add_u32 s4, s4, s1
	s_addc_u32 s5, s5, 0
	s_mov_b32 s6, 0xffffd000
	s_mov_b32 s7, -1
	s_branch .Lsc_ld_pb_dirdone

.Lsc_ld_pb_dirdone:
	v_and_b32_e32 v8, 63, v0
	s_and_b32 s1, s11, 1
	v_lshlrev_b32_e32 v8, 4, v8
	s_mul_i32 s1, s1, 0x1800
	s_nop 0
	v_add_u32_e32 v8, s1, v8
	v_mov_b32_e32 v9, v8
	v_lshrrev_b32_e32 v10, 8, v9
	v_mul_u32_u24_e32 v10, 0xaaab, v10
	v_lshrrev_b32_e32 v10, 17, v10
	v_mul_u32_u24_e32 v11, 0x600, v10
	v_sub_u32_e32 v11, 0x2d00, v11
	v_mul_lo_u32 v11, v11, s24
	v_add_u32_e32 v122, v9, v11
	v_add_u32_e32 v9, 0x400, v8
	v_lshrrev_b32_e32 v10, 8, v9
	v_mul_u32_u24_e32 v10, 0xaaab, v10
	v_lshrrev_b32_e32 v10, 17, v10
	v_mul_u32_u24_e32 v11, 0x600, v10
	v_sub_u32_e32 v11, 0x2d00, v11
	v_mul_lo_u32 v11, v11, s24
	v_add_u32_e32 v123, v9, v11
	v_add_u32_e32 v9, 0x800, v8
	v_lshrrev_b32_e32 v10, 8, v9
	v_mul_u32_u24_e32 v10, 0xaaab, v10
	v_lshrrev_b32_e32 v10, 17, v10
	v_mul_u32_u24_e32 v11, 0x600, v10
	v_sub_u32_e32 v11, 0x2d00, v11
	v_mul_lo_u32 v11, v11, s24
	v_add_u32_e32 v124, v9, v11
	v_add_u32_e32 v9, 0xc00, v8
	v_lshrrev_b32_e32 v10, 8, v9
	v_mul_u32_u24_e32 v10, 0xaaab, v10
	v_lshrrev_b32_e32 v10, 17, v10
	v_mul_u32_u24_e32 v11, 0x600, v10
	v_sub_u32_e32 v11, 0x2d00, v11
	v_mul_lo_u32 v11, v11, s24
	v_add_u32_e32 v125, v9, v11
	v_add_u32_e32 v9, 0x1000, v8
	v_lshrrev_b32_e32 v10, 8, v9
	v_mul_u32_u24_e32 v10, 0xaaab, v10
	v_lshrrev_b32_e32 v10, 17, v10
	v_mul_u32_u24_e32 v11, 0x600, v10
	v_sub_u32_e32 v11, 0x2d00, v11
	v_mul_lo_u32 v11, v11, s24
	v_add_u32_e32 v126, v9, v11
	v_add_u32_e32 v9, 0x1400, v8
	v_lshrrev_b32_e32 v10, 8, v9
	v_mul_u32_u24_e32 v10, 0xaaab, v10
	v_lshrrev_b32_e32 v10, 17, v10
	v_mul_u32_u24_e32 v11, 0x600, v10
	v_sub_u32_e32 v11, 0x2d00, v11
	v_mul_lo_u32 v11, v11, s24
	v_add_u32_e32 v127, v9, v11
	s_mul_i32 s8, s11, 0x1800
	s_add_u32 s8, s8, 0xf0
	v_writelane_b32 v130, s8, 5
	s_mov_b32 s10, 0
	s_sub_u32 s9, s23, 1
	s_mov_b32 m0, s8
	s_nop 0
	global_load_lds_dwordx4 v122, s[4:5]
	s_add_u32 m0, s8, 0x400
	s_nop 0
	global_load_lds_dwordx4 v123, s[4:5]
	s_add_u32 m0, s8, 0x800
	s_nop 0
	global_load_lds_dwordx4 v124, s[4:5]
	s_add_u32 m0, s8, 0xc00
	s_nop 0
	global_load_lds_dwordx4 v125, s[4:5]
	s_add_u32 m0, s8, 0x1000
	s_nop 0
	global_load_lds_dwordx4 v126, s[4:5]
	s_add_u32 m0, s8, 0x1400
	s_nop 0
	global_load_lds_dwordx4 v127, s[4:5]
	s_cmp_lt_u32 s10, s9
	s_cselect_b32 s1, s6, 0
	s_cselect_b32 s14, s7, 0
	s_cselect_b32 s15, 1, 0
	s_add_u32 s4, s4, s1
	s_addc_u32 s5, s5, s14
	s_add_u32 s10, s10, s15
	s_add_u32 m0, s8, 0x6000
	s_nop 0
	global_load_lds_dwordx4 v122, s[4:5]
	s_add_u32 m0, s8, 0x6400
	s_nop 0
	global_load_lds_dwordx4 v123, s[4:5]
	s_add_u32 m0, s8, 0x6800
	s_nop 0
	global_load_lds_dwordx4 v124, s[4:5]
	s_add_u32 m0, s8, 0x6c00
	s_nop 0
	global_load_lds_dwordx4 v125, s[4:5]
	s_add_u32 m0, s8, 0x7000
	s_nop 0
	global_load_lds_dwordx4 v126, s[4:5]
	s_add_u32 m0, s8, 0x7400
	s_nop 0
	global_load_lds_dwordx4 v127, s[4:5]
	s_cmp_lt_u32 s10, s9
	s_cselect_b32 s1, s6, 0
	s_cselect_b32 s14, s7, 0
	s_cselect_b32 s15, 1, 0
	s_add_u32 s4, s4, s1
	s_addc_u32 s5, s5, s14
	s_add_u32 s10, s10, s15
	s_add_u32 m0, s8, 0xc000
	s_nop 0
	global_load_lds_dwordx4 v122, s[4:5]
	s_add_u32 m0, s8, 0xc400
	s_nop 0
	global_load_lds_dwordx4 v123, s[4:5]
	s_add_u32 m0, s8, 0xc800
	s_nop 0
	global_load_lds_dwordx4 v124, s[4:5]
	s_add_u32 m0, s8, 0xcc00
	s_nop 0
	global_load_lds_dwordx4 v125, s[4:5]
	s_add_u32 m0, s8, 0xd000
	s_nop 0
	global_load_lds_dwordx4 v126, s[4:5]
	s_add_u32 m0, s8, 0xd400
	s_nop 0
	global_load_lds_dwordx4 v127, s[4:5]
	s_cmp_lt_u32 s10, s9
	s_cselect_b32 s1, s6, 0
	s_cselect_b32 s14, s7, 0
	s_cselect_b32 s15, 1, 0
	s_add_u32 s4, s4, s1
	s_addc_u32 s5, s5, s14
	s_add_u32 s10, s10, s15
	s_add_u32 m0, s8, 0x12000
	s_nop 0
	global_load_lds_dwordx4 v122, s[4:5]
	s_add_u32 m0, s8, 0x12400
	s_nop 0
	global_load_lds_dwordx4 v123, s[4:5]
	s_add_u32 m0, s8, 0x12800
	s_nop 0
	global_load_lds_dwordx4 v124, s[4:5]
	s_add_u32 m0, s8, 0x12c00
	s_nop 0
	global_load_lds_dwordx4 v125, s[4:5]
	s_add_u32 m0, s8, 0x13000
	s_nop 0
	global_load_lds_dwordx4 v126, s[4:5]
	s_add_u32 m0, s8, 0x13400
	s_nop 0
	global_load_lds_dwordx4 v127, s[4:5]
	s_cmp_lt_u32 s10, s9
	s_cselect_b32 s1, s6, 0
	s_cselect_b32 s14, s7, 0
	s_cselect_b32 s15, 1, 0
	s_add_u32 s4, s4, s1
	s_addc_u32 s5, s5, s14
	s_add_u32 s10, s10, s15
	v_writelane_b32 v130, s4, 0
	v_writelane_b32 v130, s5, 1
	v_writelane_b32 v130, s10, 2
	v_writelane_b32 v130, s6, 3
	v_writelane_b32 v130, s7, 4
	s_and_b32 s22, s20, 1
	s_lshl_b32 s22, s22, 5
	s_lshl_b32 s1, s0, 3
	s_add_u32 s22, s22, s1
	v_and_b32_e32 v116, 15, v0
	v_bfe_u32 v117, v0, 4, 2
	v_lshlrev_b32_e32 v111, 4, v116
	v_add_u32_e32 v118, s22, v117
	v_add_u32_e32 v111, 0xf0, v111
	v_lshlrev_b32_e32 v112, 2, v118
	v_add_u32_e32 v112, 0x2f0, v112
	v_lshlrev_b32_e32 v114, 8, v118
	v_lshl_add_u32 v114, v116, 4, v114
	s_lshr_b32 s1, s21, 2
	s_and_b32 s4, s21, 3
	s_lshl_b32 s1, s1, 1
	s_add_u32 s1, s1, s80
	s_lshl_b32 s1, s1, 1
	s_add_u32 s1, s1, s24
	s_lshl_b32 s1, s1, 2
	s_add_u32 s1, s1, s4
	s_lshl_b32 s1, s1, 14
	s_cmp_lt_u32 s71, 64
	s_cbranch_scc0 .Lsc_ctx_init_pb
	ds_read_b64 v[120:121], v131 offset:32
	s_waitcnt lgkmcnt(0)
	v_readfirstlane_b32 s4, v120
	v_readfirstlane_b32 s5, v121
	s_nop 3
	s_add_u32 s4, s4, s1
	s_addc_u32 s5, s5, 0
	s_nop 3
	global_load_dwordx4 v[2:5], v114, s[4:5]
	global_load_dwordx4 v[6:9], v114, s[4:5] offset:1024
	s_lshl_b32 s6, s21, 2
	s_lshr_b32 s6, s21, 2
	s_lshl_b32 s6, s6, 20
	s_add_u32 s6, s6, 0x400000
	s_branch .Lsc_init_done_pb

.Lsc_init_done_pb:
	s_mov_b32 s9, s1
	v_readlane_b32 s4, v253, 47
	v_readlane_b32 s5, v253, 48
	s_lshl_b32 s1, s24, 23
	s_add_u32 s6, s6, s1
	s_and_b32 s1, s21, 3
	s_lshl_b32 s1, s1, 8
	s_add_u32 s6, s6, s1
	s_lshl_b32 s1, s22, 2
	s_add_u32 s6, s6, s1
	s_add_u32 s4, s4, s6
	s_addc_u32 s5, s5, 0
	s_cmp_eq_u32 s24, 1
	s_cselect_b64 s[10:11], -1, 0
	s_mov_b32 s6, 0x4000
	s_cselect_b32 s6, 0xffffc000, s6
	s_cselect_b32 s7, -1, 0
	s_lshl_b32 s1, s23, 4
	s_sub_u32 s1, s1, 1
	v_sub_u32_e32 v119, s1, v116
	v_cndmask_b32_e64 v119, v116, v119, s[10:11]
	v_lshlrev_b32_e32 v119, 10, v119
	v_lshl_add_u32 v113, v117, 2, v119
	s_mov_b32 s10, 0xcccccccc
	s_mov_b32 s11, 0xcccccccc
	s_mov_b32 s14, 0xaaaaaaaa
	s_mov_b32 s15, 0xaaaaaaaa
	s_mov_b32 s8, 0
	s_mov_b32 s1, s23
	v_mov_b32_e32 v106, v111
	v_mov_b32_e32 v107, v112
	s_waitcnt vmcnt(12)
	s_barrier
	ds_read_b128 v[10:13], v106 offset:256
	ds_read_b128 v[14:17], v106 offset:12288
	ds_read_b128 v[18:21], v106 offset:12544
	ds_read_b128 v[22:25], v106 offset:12800
	ds_read_b128 v[26:29], v106 offset:0
	ds_read_b32 v30, v107 offset:0
	ds_read_b32 v32, v107 offset:16
	ds_read_b128 v[34:37], v106 offset:1024
	ds_read_b128 v[38:41], v106 offset:13056
	ds_read_b128 v[42:45], v106 offset:13312
	ds_read_b128 v[46:49], v106 offset:13568
	ds_read_b128 v[50:53], v106 offset:768
	ds_read_b32 v54, v107 offset:768
	ds_read_b32 v56, v107 offset:784
.Lsc_c_loop_pb:
	s_waitcnt vmcnt(12)
	s_barrier
	s_add_u32 s14, s8, 0x18000
	s_mov_b32 s15, 0x1e000
	s_cmp_lt_u32 s14, s15
	s_cselect_b32 s15, 0, s15
	s_sub_u32 s14, s14, s15
	v_readlane_b32 s15, v130, 5
	v_readlane_b32 s10, v130, 0
	v_readlane_b32 s11, v130, 1
	s_add_u32 s14, s14, s15
	s_nop 4
	s_mov_b32 m0, s14
	s_nop 0
	global_load_lds_dwordx4 v122, s[10:11]
	s_add_u32 m0, s14, 0x400
	s_nop 0
	global_load_lds_dwordx4 v123, s[10:11]
	s_add_u32 m0, s14, 0x800
	s_nop 0
	global_load_lds_dwordx4 v124, s[10:11]
	s_add_u32 m0, s14, 0xc00
	s_nop 0
	global_load_lds_dwordx4 v125, s[10:11]
	s_add_u32 m0, s14, 0x1000
	s_nop 0
	global_load_lds_dwordx4 v126, s[10:11]
	s_add_u32 m0, s14, 0x1400
	s_nop 0
	global_load_lds_dwordx4 v127, s[10:11]
	v_readlane_b32 s15, v130, 2
	v_readlane_b32 s14, v130, 3
	v_readlane_b32 s20, v130, 4
	s_sub_u32 m0, s23, 1
	s_cmp_lt_u32 s15, m0
	s_cselect_b32 s14, s14, 0
	s_cselect_b32 s20, s20, 0
	s_addc_u32 s15, s15, 0
	s_add_u32 s10, s10, s14
	s_addc_u32 s11, s11, s20
	v_writelane_b32 v130, s10, 0
	v_writelane_b32 v130, s11, 1
	v_writelane_b32 v130, s15, 2
	s_mov_b32 s10, 0xcccccccc
	s_mov_b32 s11, 0xcccccccc
	s_mov_b32 s14, 0xaaaaaaaa
	s_mov_b32 s15, 0xaaaaaaaa
	s_add_u32 s20, s8, 0x6000
	s_cmp_eq_u32 s20, 0x1e000
	s_cselect_b32 s20, 0, s20
	v_add_u32_e32 v108, s20, v111
	v_add_u32_e32 v109, s20, v112
	s_waitcnt lgkmcnt(7)
	v_pk_mul_f32 v[86:87], v[4:5], v[12:13]
	v_pk_mul_f32 v[90:91], v[8:9], v[12:13]
	v_pk_fma_f32 v[86:87], v[2:3], v[10:11], v[86:87]
	v_pk_fma_f32 v[90:91], v[6:7], v[10:11], v[90:91]
	v_add_f32_e32 v82, v86, v87
	v_add_f32_e32 v84, v90, v91
	ds_read_b128 v[58:61], v106 offset:1792
	v_add_f32_dpp v82, v82, v82 row_ror:8 row_mask:0xf bank_mask:0xf
	v_add_f32_dpp v84, v84, v84 row_ror:8 row_mask:0xf bank_mask:0xf
	ds_read_b128 v[62:65], v106 offset:13824
	v_add_f32_dpp v82, v82, v82 row_ror:4 row_mask:0xf bank_mask:0xf
	v_add_f32_dpp v84, v84, v84 row_ror:4 row_mask:0xf bank_mask:0xf
	v_pk_mul_f32 v[98:99], v[24:25], v[30:31] op_sel_hi:[1,0]
	v_add_f32_dpp v82, v82, v82 row_ror:2 row_mask:0xf bank_mask:0xf
	v_add_f32_dpp v84, v84, v84 row_ror:2 row_mask:0xf bank_mask:0xf
	v_pk_mul_f32 v[102:103], v[24:25], v[32:33] op_sel_hi:[1,0]
	ds_read_b128 v[66:69], v106 offset:14080
	ds_read_b128 v[70:73], v106 offset:14336
	v_pk_mul_f32 v[96:97], v[22:23], v[30:31] op_sel_hi:[1,0]
	v_pk_fma_f32 v[98:99], v[4:5], v[16:17], v[98:99]
	v_pk_mul_f32 v[100:101], v[22:23], v[32:33] op_sel_hi:[1,0]
	v_pk_fma_f32 v[102:103], v[8:9], v[16:17], v[102:103]
	ds_read_b128 v[74:77], v106 offset:1536
	v_add_f32_dpp v82, v82, v82 row_ror:1 row_mask:0xf bank_mask:0xf
	v_add_f32_dpp v84, v84, v84 row_ror:1 row_mask:0xf bank_mask:0xf
	ds_read_b32 v78, v107 offset:1536
	v_pk_fma_f32 v[96:97], v[2:3], v[14:15], v[96:97]
	v_pk_fma_f32 v[4:5], v[20:21], v[82:83], v[98:99] op_sel_hi:[1,0,1]
	v_pk_fma_f32 v[100:101], v[6:7], v[14:15], v[100:101]
	v_pk_fma_f32 v[8:9], v[20:21], v[84:85], v[102:103] op_sel_hi:[1,0,1]
	ds_read_b32 v80, v107 offset:1552
	s_waitcnt lgkmcnt(7)
	v_pk_fma_f32 v[2:3], v[18:19], v[82:83], v[96:97] op_sel_hi:[1,0,1]
	v_pk_fma_f32 v[6:7], v[18:19], v[84:85], v[100:101] op_sel_hi:[1,0,1]
	v_pk_mul_f32 v[86:87], v[4:5], v[36:37]
	v_pk_mul_f32 v[90:91], v[8:9], v[36:37]
	v_pk_fma_f32 v[86:87], v[2:3], v[34:35], v[86:87]
	v_pk_fma_f32 v[90:91], v[6:7], v[34:35], v[90:91]
	v_add_f32_e32 v82, v86, v87
	v_add_f32_e32 v84, v90, v91
	ds_read_b128 v[136:139], v106 offset:2560
	v_add_f32_dpp v82, v82, v82 row_ror:8 row_mask:0xf bank_mask:0xf
	v_add_f32_dpp v84, v84, v84 row_ror:8 row_mask:0xf bank_mask:0xf
	ds_read_b128 v[140:143], v106 offset:14592
	v_add_f32_dpp v82, v82, v82 row_ror:4 row_mask:0xf bank_mask:0xf
	v_add_f32_dpp v84, v84, v84 row_ror:4 row_mask:0xf bank_mask:0xf
	v_pk_mul_f32 v[98:99], v[48:49], v[54:55] op_sel_hi:[1,0]
	v_add_f32_dpp v82, v82, v82 row_ror:2 row_mask:0xf bank_mask:0xf
	v_add_f32_dpp v84, v84, v84 row_ror:2 row_mask:0xf bank_mask:0xf
	v_pk_mul_f32 v[102:103], v[48:49], v[56:57] op_sel_hi:[1,0]
	ds_read_b128 v[144:147], v106 offset:14848
	ds_read_b128 v[148:151], v106 offset:15104
	v_pk_mul_f32 v[96:97], v[46:47], v[54:55] op_sel_hi:[1,0]
	v_pk_fma_f32 v[98:99], v[4:5], v[40:41], v[98:99]
	v_pk_mul_f32 v[100:101], v[46:47], v[56:57] op_sel_hi:[1,0]
	v_pk_fma_f32 v[102:103], v[8:9], v[40:41], v[102:103]
	ds_read_b128 v[152:155], v106 offset:2304
	v_pk_mul_f32 v[92:93], v[4:5], v[28:29]
	v_pk_mul_f32 v[94:95], v[8:9], v[28:29]
	v_add_f32_dpp v82, v82, v82 row_ror:1 row_mask:0xf bank_mask:0xf
	v_add_f32_dpp v84, v84, v84 row_ror:1 row_mask:0xf bank_mask:0xf
	ds_read_b32 v156, v107 offset:2304
	v_pk_fma_f32 v[96:97], v[2:3], v[38:39], v[96:97]
	v_pk_fma_f32 v[4:5], v[44:45], v[82:83], v[98:99] op_sel_hi:[1,0,1]
	v_pk_fma_f32 v[100:101], v[6:7], v[38:39], v[100:101]
	v_pk_fma_f32 v[8:9], v[44:45], v[84:85], v[102:103] op_sel_hi:[1,0,1]
	ds_read_b32 v158, v107 offset:2320
	v_pk_fma_f32 v[92:93], v[2:3], v[26:27], v[92:93]
	v_pk_fma_f32 v[94:95], v[6:7], v[26:27], v[94:95]
	s_waitcnt lgkmcnt(7)
	v_pk_fma_f32 v[2:3], v[42:43], v[82:83], v[96:97] op_sel_hi:[1,0,1]
	v_pk_fma_f32 v[6:7], v[42:43], v[84:85], v[100:101] op_sel_hi:[1,0,1]
	v_pk_mul_f32 v[86:87], v[4:5], v[60:61]
	v_pk_mul_f32 v[90:91], v[8:9], v[60:61]
	v_pk_fma_f32 v[86:87], v[2:3], v[58:59], v[86:87]
	v_pk_fma_f32 v[90:91], v[6:7], v[58:59], v[90:91]
	v_add_f32_e32 v82, v86, v87
	v_add_f32_e32 v84, v90, v91
	v_pk_mul_f32 v[98:99], v[72:73], v[78:79] op_sel_hi:[1,0]
	v_add_f32_dpp v82, v82, v82 row_ror:8 row_mask:0xf bank_mask:0xf
	v_add_f32_dpp v84, v84, v84 row_ror:8 row_mask:0xf bank_mask:0xf
	v_add_f32_e32 v160, v92, v93
	v_add_f32_dpp v82, v82, v82 row_ror:4 row_mask:0xf bank_mask:0xf
	v_add_f32_dpp v84, v84, v84 row_ror:4 row_mask:0xf bank_mask:0xf
	v_pk_mul_f32 v[102:103], v[72:73], v[80:81] op_sel_hi:[1,0]
	v_add_f32_dpp v82, v82, v82 row_ror:2 row_mask:0xf bank_mask:0xf
	v_add_f32_dpp v84, v84, v84 row_ror:2 row_mask:0xf bank_mask:0xf
	v_add_f32_e32 v190, v94, v95
	ds_read_b128 v[10:13], v106 offset:3328
	ds_read_b128 v[14:17], v106 offset:15360
	ds_read_b128 v[18:21], v106 offset:15616
	ds_read_b128 v[22:25], v106 offset:15872
	v_pk_mul_f32 v[96:97], v[70:71], v[78:79] op_sel_hi:[1,0]
	v_pk_fma_f32 v[98:99], v[4:5], v[64:65], v[98:99]
	v_pk_mul_f32 v[100:101], v[70:71], v[80:81] op_sel_hi:[1,0]
	v_pk_fma_f32 v[102:103], v[8:9], v[64:65], v[102:103]
	ds_read_b128 v[26:29], v106 offset:3072
	v_pk_mul_f32 v[92:93], v[4:5], v[52:53]
	v_pk_mul_f32 v[94:95], v[8:9], v[52:53]
	v_add_f32_dpp v82, v82, v82 row_ror:1 row_mask:0xf bank_mask:0xf
	v_add_f32_dpp v84, v84, v84 row_ror:1 row_mask:0xf bank_mask:0xf
	ds_read_b32 v30, v107 offset:3072
	v_pk_fma_f32 v[96:97], v[2:3], v[62:63], v[96:97]
	v_pk_fma_f32 v[4:5], v[68:69], v[82:83], v[98:99] op_sel_hi:[1,0,1]
	v_pk_fma_f32 v[100:101], v[6:7], v[62:63], v[100:101]
	v_pk_fma_f32 v[8:9], v[68:69], v[84:85], v[102:103] op_sel_hi:[1,0,1]
	ds_read_b32 v32, v107 offset:3088
	v_pk_fma_f32 v[92:93], v[2:3], v[50:51], v[92:93]
	v_pk_fma_f32 v[94:95], v[6:7], v[50:51], v[94:95]
	s_waitcnt lgkmcnt(7)
	v_pk_fma_f32 v[2:3], v[66:67], v[82:83], v[96:97] op_sel_hi:[1,0,1]
	v_pk_fma_f32 v[6:7], v[66:67], v[84:85], v[100:101] op_sel_hi:[1,0,1]
	v_pk_mul_f32 v[86:87], v[4:5], v[138:139]
	v_pk_mul_f32 v[90:91], v[8:9], v[138:139]
	v_pk_fma_f32 v[86:87], v[2:3], v[136:137], v[86:87]
	v_pk_fma_f32 v[90:91], v[6:7], v[136:137], v[90:91]
	v_add_f32_e32 v82, v86, v87
	v_add_f32_e32 v84, v90, v91
	v_pk_mul_f32 v[98:99], v[150:151], v[156:157] op_sel_hi:[1,0]
	v_add_f32_dpp v82, v82, v82 row_ror:8 row_mask:0xf bank_mask:0xf
	v_add_f32_dpp v84, v84, v84 row_ror:8 row_mask:0xf bank_mask:0xf
	v_add_f32_e32 v161, v92, v93
	v_add_f32_dpp v82, v82, v82 row_ror:4 row_mask:0xf bank_mask:0xf
	v_add_f32_dpp v84, v84, v84 row_ror:4 row_mask:0xf bank_mask:0xf
	v_pk_mul_f32 v[102:103], v[150:151], v[158:159] op_sel_hi:[1,0]
	v_add_f32_dpp v82, v82, v82 row_ror:2 row_mask:0xf bank_mask:0xf
	v_add_f32_dpp v84, v84, v84 row_ror:2 row_mask:0xf bank_mask:0xf
	v_add_f32_e32 v191, v94, v95
	ds_read_b128 v[34:37], v106 offset:4096
	ds_read_b128 v[38:41], v106 offset:16128
	ds_read_b128 v[42:45], v106 offset:16384
	ds_read_b128 v[46:49], v106 offset:16640
	v_pk_mul_f32 v[96:97], v[148:149], v[156:157] op_sel_hi:[1,0]
	v_pk_fma_f32 v[98:99], v[4:5], v[142:143], v[98:99]
	v_pk_mul_f32 v[100:101], v[148:149], v[158:159] op_sel_hi:[1,0]
	v_pk_fma_f32 v[102:103], v[8:9], v[142:143], v[102:103]
	ds_read_b128 v[50:53], v106 offset:3840
	v_pk_mul_f32 v[92:93], v[4:5], v[76:77]
	v_pk_mul_f32 v[94:95], v[8:9], v[76:77]
	v_add_f32_dpp v82, v82, v82 row_ror:1 row_mask:0xf bank_mask:0xf
	v_add_f32_dpp v84, v84, v84 row_ror:1 row_mask:0xf bank_mask:0xf
	ds_read_b32 v54, v107 offset:3840
	v_pk_fma_f32 v[96:97], v[2:3], v[140:141], v[96:97]
	v_pk_fma_f32 v[4:5], v[146:147], v[82:83], v[98:99] op_sel_hi:[1,0,1]
	v_pk_fma_f32 v[100:101], v[6:7], v[140:141], v[100:101]
	v_pk_fma_f32 v[8:9], v[146:147], v[84:85], v[102:103] op_sel_hi:[1,0,1]
	ds_read_b32 v56, v107 offset:3856
	v_pk_fma_f32 v[92:93], v[2:3], v[74:75], v[92:93]
	v_pk_fma_f32 v[94:95], v[6:7], v[74:75], v[94:95]
	s_waitcnt lgkmcnt(7)
	v_pk_fma_f32 v[2:3], v[144:145], v[82:83], v[96:97] op_sel_hi:[1,0,1]
	v_pk_fma_f32 v[6:7], v[144:145], v[84:85], v[100:101] op_sel_hi:[1,0,1]
	v_pk_mul_f32 v[86:87], v[4:5], v[12:13]
	v_pk_mul_f32 v[90:91], v[8:9], v[12:13]
	v_pk_fma_f32 v[86:87], v[2:3], v[10:11], v[86:87]
	v_pk_fma_f32 v[90:91], v[6:7], v[10:11], v[90:91]
	v_add_f32_e32 v82, v86, v87
	v_add_f32_e32 v84, v90, v91
	v_pk_mul_f32 v[98:99], v[24:25], v[30:31] op_sel_hi:[1,0]
	v_add_f32_dpp v82, v82, v82 row_ror:8 row_mask:0xf bank_mask:0xf
	v_add_f32_dpp v84, v84, v84 row_ror:8 row_mask:0xf bank_mask:0xf
	v_add_f32_e32 v162, v92, v93
	v_add_f32_dpp v82, v82, v82 row_ror:4 row_mask:0xf bank_mask:0xf
	v_add_f32_dpp v84, v84, v84 row_ror:4 row_mask:0xf bank_mask:0xf
	v_pk_mul_f32 v[102:103], v[24:25], v[32:33] op_sel_hi:[1,0]
	v_add_f32_dpp v82, v82, v82 row_ror:2 row_mask:0xf bank_mask:0xf
	v_add_f32_dpp v84, v84, v84 row_ror:2 row_mask:0xf bank_mask:0xf
	v_add_f32_e32 v192, v94, v95
	ds_read_b128 v[58:61], v106 offset:4864
	ds_read_b128 v[62:65], v106 offset:16896
	ds_read_b128 v[66:69], v106 offset:17152
	ds_read_b128 v[70:73], v106 offset:17408
	v_pk_mul_f32 v[96:97], v[22:23], v[30:31] op_sel_hi:[1,0]
	v_pk_fma_f32 v[98:99], v[4:5], v[16:17], v[98:99]
	v_pk_mul_f32 v[100:101], v[22:23], v[32:33] op_sel_hi:[1,0]
	v_pk_fma_f32 v[102:103], v[8:9], v[16:17], v[102:103]
	ds_read_b128 v[74:77], v106 offset:4608
	v_pk_mul_f32 v[92:93], v[4:5], v[154:155]
	v_pk_mul_f32 v[94:95], v[8:9], v[154:155]
	v_add_f32_dpp v82, v82, v82 row_ror:1 row_mask:0xf bank_mask:0xf
	v_add_f32_dpp v84, v84, v84 row_ror:1 row_mask:0xf bank_mask:0xf
	ds_read_b32 v78, v107 offset:4608
	v_pk_fma_f32 v[96:97], v[2:3], v[14:15], v[96:97]
	v_pk_fma_f32 v[4:5], v[20:21], v[82:83], v[98:99] op_sel_hi:[1,0,1]
	v_pk_fma_f32 v[100:101], v[6:7], v[14:15], v[100:101]
	v_pk_fma_f32 v[8:9], v[20:21], v[84:85], v[102:103] op_sel_hi:[1,0,1]
	ds_read_b32 v80, v107 offset:4624
	v_pk_fma_f32 v[92:93], v[2:3], v[152:153], v[92:93]
	v_pk_fma_f32 v[94:95], v[6:7], v[152:153], v[94:95]
	s_waitcnt lgkmcnt(7)
	v_pk_fma_f32 v[2:3], v[18:19], v[82:83], v[96:97] op_sel_hi:[1,0,1]
	v_pk_fma_f32 v[6:7], v[18:19], v[84:85], v[100:101] op_sel_hi:[1,0,1]
	v_pk_mul_f32 v[86:87], v[4:5], v[36:37]
	v_pk_mul_f32 v[90:91], v[8:9], v[36:37]
	v_pk_fma_f32 v[86:87], v[2:3], v[34:35], v[86:87]
	v_pk_fma_f32 v[90:91], v[6:7], v[34:35], v[90:91]
	v_add_f32_e32 v82, v86, v87
	v_add_f32_e32 v84, v90, v91
	v_pk_mul_f32 v[98:99], v[48:49], v[54:55] op_sel_hi:[1,0]
	v_add_f32_dpp v82, v82, v82 row_ror:8 row_mask:0xf bank_mask:0xf
	v_add_f32_dpp v84, v84, v84 row_ror:8 row_mask:0xf bank_mask:0xf
	v_add_f32_e32 v163, v92, v93
	v_add_f32_dpp v82, v82, v82 row_ror:4 row_mask:0xf bank_mask:0xf
	v_add_f32_dpp v84, v84, v84 row_ror:4 row_mask:0xf bank_mask:0xf
	v_pk_mul_f32 v[102:103], v[48:49], v[56:57] op_sel_hi:[1,0]
	v_add_f32_dpp v82, v82, v82 row_ror:2 row_mask:0xf bank_mask:0xf
	v_add_f32_dpp v84, v84, v84 row_ror:2 row_mask:0xf bank_mask:0xf
	v_add_f32_e32 v193, v94, v95
	ds_read_b128 v[136:139], v106 offset:5632
	ds_read_b128 v[140:143], v106 offset:17664
	ds_read_b128 v[144:147], v106 offset:17920
	ds_read_b128 v[148:151], v106 offset:18176
	v_pk_mul_f32 v[96:97], v[46:47], v[54:55] op_sel_hi:[1,0]
	v_pk_fma_f32 v[98:99], v[4:5], v[40:41], v[98:99]
	v_pk_mul_f32 v[100:101], v[46:47], v[56:57] op_sel_hi:[1,0]
	v_pk_fma_f32 v[102:103], v[8:9], v[40:41], v[102:103]
	ds_read_b128 v[152:155], v106 offset:5376
	v_pk_mul_f32 v[92:93], v[4:5], v[28:29]
	v_pk_mul_f32 v[94:95], v[8:9], v[28:29]
	v_add_f32_dpp v82, v82, v82 row_ror:1 row_mask:0xf bank_mask:0xf
	v_add_f32_dpp v84, v84, v84 row_ror:1 row_mask:0xf bank_mask:0xf
	ds_read_b32 v156, v107 offset:5376
	v_pk_fma_f32 v[96:97], v[2:3], v[38:39], v[96:97]
	v_pk_fma_f32 v[4:5], v[44:45], v[82:83], v[98:99] op_sel_hi:[1,0,1]
	v_pk_fma_f32 v[100:101], v[6:7], v[38:39], v[100:101]
	v_pk_fma_f32 v[8:9], v[44:45], v[84:85], v[102:103] op_sel_hi:[1,0,1]
	ds_read_b32 v158, v107 offset:5392
	v_pk_fma_f32 v[92:93], v[2:3], v[26:27], v[92:93]
	v_pk_fma_f32 v[94:95], v[6:7], v[26:27], v[94:95]
	s_waitcnt lgkmcnt(7)
	v_pk_fma_f32 v[2:3], v[42:43], v[82:83], v[96:97] op_sel_hi:[1,0,1]
	v_pk_fma_f32 v[6:7], v[42:43], v[84:85], v[100:101] op_sel_hi:[1,0,1]
	v_pk_mul_f32 v[86:87], v[4:5], v[60:61]
	v_pk_mul_f32 v[90:91], v[8:9], v[60:61]
	v_pk_fma_f32 v[86:87], v[2:3], v[58:59], v[86:87]
	v_pk_fma_f32 v[90:91], v[6:7], v[58:59], v[90:91]
	v_add_f32_e32 v82, v86, v87
	v_add_f32_e32 v84, v90, v91
	v_pk_mul_f32 v[98:99], v[72:73], v[78:79] op_sel_hi:[1,0]
	v_add_f32_dpp v82, v82, v82 row_ror:8 row_mask:0xf bank_mask:0xf
	v_add_f32_dpp v84, v84, v84 row_ror:8 row_mask:0xf bank_mask:0xf
	v_add_f32_e32 v164, v92, v93
	v_add_f32_dpp v82, v82, v82 row_ror:4 row_mask:0xf bank_mask:0xf
	v_add_f32_dpp v84, v84, v84 row_ror:4 row_mask:0xf bank_mask:0xf
	v_pk_mul_f32 v[102:103], v[72:73], v[80:81] op_sel_hi:[1,0]
	v_add_f32_dpp v82, v82, v82 row_ror:2 row_mask:0xf bank_mask:0xf
	v_add_f32_dpp v84, v84, v84 row_ror:2 row_mask:0xf bank_mask:0xf
	v_add_f32_e32 v194, v94, v95
	ds_read_b128 v[10:13], v106 offset:6400
	ds_read_b128 v[14:17], v106 offset:18432
	ds_read_b128 v[18:21], v106 offset:18688
	ds_read_b128 v[22:25], v106 offset:18944
	v_pk_mul_f32 v[96:97], v[70:71], v[78:79] op_sel_hi:[1,0]
	v_pk_fma_f32 v[98:99], v[4:5], v[64:65], v[98:99]
	v_pk_mul_f32 v[100:101], v[70:71], v[80:81] op_sel_hi:[1,0]
	v_pk_fma_f32 v[102:103], v[8:9], v[64:65], v[102:103]
	ds_read_b128 v[26:29], v106 offset:6144
	v_pk_mul_f32 v[92:93], v[4:5], v[52:53]
	v_pk_mul_f32 v[94:95], v[8:9], v[52:53]
	v_add_f32_dpp v82, v82, v82 row_ror:1 row_mask:0xf bank_mask:0xf
	v_add_f32_dpp v84, v84, v84 row_ror:1 row_mask:0xf bank_mask:0xf
	ds_read_b32 v30, v107 offset:6144
	v_pk_fma_f32 v[96:97], v[2:3], v[62:63], v[96:97]
	v_pk_fma_f32 v[4:5], v[68:69], v[82:83], v[98:99] op_sel_hi:[1,0,1]
	v_pk_fma_f32 v[100:101], v[6:7], v[62:63], v[100:101]
	v_pk_fma_f32 v[8:9], v[68:69], v[84:85], v[102:103] op_sel_hi:[1,0,1]
	ds_read_b32 v32, v107 offset:6160
	v_pk_fma_f32 v[92:93], v[2:3], v[50:51], v[92:93]
	v_pk_fma_f32 v[94:95], v[6:7], v[50:51], v[94:95]
	s_waitcnt lgkmcnt(7)
	v_pk_fma_f32 v[2:3], v[66:67], v[82:83], v[96:97] op_sel_hi:[1,0,1]
	v_pk_fma_f32 v[6:7], v[66:67], v[84:85], v[100:101] op_sel_hi:[1,0,1]
	v_pk_mul_f32 v[86:87], v[4:5], v[138:139]
	v_pk_mul_f32 v[90:91], v[8:9], v[138:139]
	v_pk_fma_f32 v[86:87], v[2:3], v[136:137], v[86:87]
	v_pk_fma_f32 v[90:91], v[6:7], v[136:137], v[90:91]
	v_add_f32_e32 v82, v86, v87
	v_add_f32_e32 v84, v90, v91
	v_pk_mul_f32 v[98:99], v[150:151], v[156:157] op_sel_hi:[1,0]
	v_add_f32_dpp v82, v82, v82 row_ror:8 row_mask:0xf bank_mask:0xf
	v_add_f32_dpp v84, v84, v84 row_ror:8 row_mask:0xf bank_mask:0xf
	v_add_f32_e32 v165, v92, v93
	v_add_f32_dpp v82, v82, v82 row_ror:4 row_mask:0xf bank_mask:0xf
	v_add_f32_dpp v84, v84, v84 row_ror:4 row_mask:0xf bank_mask:0xf
	v_pk_mul_f32 v[102:103], v[150:151], v[158:159] op_sel_hi:[1,0]
	v_add_f32_dpp v82, v82, v82 row_ror:2 row_mask:0xf bank_mask:0xf
	v_add_f32_dpp v84, v84, v84 row_ror:2 row_mask:0xf bank_mask:0xf
	v_add_f32_e32 v195, v94, v95
	ds_read_b128 v[34:37], v106 offset:7168
	ds_read_b128 v[38:41], v106 offset:19200
	ds_read_b128 v[42:45], v106 offset:19456
	ds_read_b128 v[46:49], v106 offset:19712
	v_pk_mul_f32 v[96:97], v[148:149], v[156:157] op_sel_hi:[1,0]
	v_pk_fma_f32 v[98:99], v[4:5], v[142:143], v[98:99]
	v_pk_mul_f32 v[100:101], v[148:149], v[158:159] op_sel_hi:[1,0]
	v_pk_fma_f32 v[102:103], v[8:9], v[142:143], v[102:103]
	ds_read_b128 v[50:53], v106 offset:6912
	v_pk_mul_f32 v[92:93], v[4:5], v[76:77]
	v_pk_mul_f32 v[94:95], v[8:9], v[76:77]
	v_add_f32_dpp v82, v82, v82 row_ror:1 row_mask:0xf bank_mask:0xf
	v_add_f32_dpp v84, v84, v84 row_ror:1 row_mask:0xf bank_mask:0xf
	ds_read_b32 v54, v107 offset:6912
	v_pk_fma_f32 v[96:97], v[2:3], v[140:141], v[96:97]
	v_pk_fma_f32 v[4:5], v[146:147], v[82:83], v[98:99] op_sel_hi:[1,0,1]
	v_pk_fma_f32 v[100:101], v[6:7], v[140:141], v[100:101]
	v_pk_fma_f32 v[8:9], v[146:147], v[84:85], v[102:103] op_sel_hi:[1,0,1]
	ds_read_b32 v56, v107 offset:6928
	v_pk_fma_f32 v[92:93], v[2:3], v[74:75], v[92:93]
	v_pk_fma_f32 v[94:95], v[6:7], v[74:75], v[94:95]
	s_waitcnt lgkmcnt(7)
	v_pk_fma_f32 v[2:3], v[144:145], v[82:83], v[96:97] op_sel_hi:[1,0,1]
	v_pk_fma_f32 v[6:7], v[144:145], v[84:85], v[100:101] op_sel_hi:[1,0,1]
	v_pk_mul_f32 v[86:87], v[4:5], v[12:13]
	v_pk_mul_f32 v[90:91], v[8:9], v[12:13]
	v_pk_fma_f32 v[86:87], v[2:3], v[10:11], v[86:87]
	v_pk_fma_f32 v[90:91], v[6:7], v[10:11], v[90:91]
	v_add_f32_e32 v82, v86, v87
	v_add_f32_e32 v84, v90, v91
	v_pk_mul_f32 v[98:99], v[24:25], v[30:31] op_sel_hi:[1,0]
	v_add_f32_dpp v82, v82, v82 row_ror:8 row_mask:0xf bank_mask:0xf
	v_add_f32_dpp v84, v84, v84 row_ror:8 row_mask:0xf bank_mask:0xf
	v_add_f32_e32 v166, v92, v93
	v_add_f32_dpp v82, v82, v82 row_ror:4 row_mask:0xf bank_mask:0xf
	v_add_f32_dpp v84, v84, v84 row_ror:4 row_mask:0xf bank_mask:0xf
	v_pk_mul_f32 v[102:103], v[24:25], v[32:33] op_sel_hi:[1,0]
	v_add_f32_dpp v82, v82, v82 row_ror:2 row_mask:0xf bank_mask:0xf
	v_add_f32_dpp v84, v84, v84 row_ror:2 row_mask:0xf bank_mask:0xf
	v_add_f32_e32 v196, v94, v95
	ds_read_b128 v[58:61], v106 offset:7936
	ds_read_b128 v[62:65], v106 offset:19968
	ds_read_b128 v[66:69], v106 offset:20224
	ds_read_b128 v[70:73], v106 offset:20480
	v_pk_mul_f32 v[96:97], v[22:23], v[30:31] op_sel_hi:[1,0]
	v_pk_fma_f32 v[98:99], v[4:5], v[16:17], v[98:99]
	v_pk_mul_f32 v[100:101], v[22:23], v[32:33] op_sel_hi:[1,0]
	v_pk_fma_f32 v[102:103], v[8:9], v[16:17], v[102:103]
	ds_read_b128 v[74:77], v106 offset:7680
	v_pk_mul_f32 v[92:93], v[4:5], v[154:155]
	v_pk_mul_f32 v[94:95], v[8:9], v[154:155]
	v_add_f32_dpp v82, v82, v82 row_ror:1 row_mask:0xf bank_mask:0xf
	v_add_f32_dpp v84, v84, v84 row_ror:1 row_mask:0xf bank_mask:0xf
	ds_read_b32 v78, v107 offset:7680
	v_pk_fma_f32 v[96:97], v[2:3], v[14:15], v[96:97]
	v_pk_fma_f32 v[4:5], v[20:21], v[82:83], v[98:99] op_sel_hi:[1,0,1]
	v_pk_fma_f32 v[100:101], v[6:7], v[14:15], v[100:101]
	v_pk_fma_f32 v[8:9], v[20:21], v[84:85], v[102:103] op_sel_hi:[1,0,1]
	ds_read_b32 v80, v107 offset:7696
	v_pk_fma_f32 v[92:93], v[2:3], v[152:153], v[92:93]
	v_pk_fma_f32 v[94:95], v[6:7], v[152:153], v[94:95]
	s_waitcnt lgkmcnt(7)
	v_pk_fma_f32 v[2:3], v[18:19], v[82:83], v[96:97] op_sel_hi:[1,0,1]
	v_pk_fma_f32 v[6:7], v[18:19], v[84:85], v[100:101] op_sel_hi:[1,0,1]
	v_pk_mul_f32 v[86:87], v[4:5], v[36:37]
	v_pk_mul_f32 v[90:91], v[8:9], v[36:37]
	v_pk_fma_f32 v[86:87], v[2:3], v[34:35], v[86:87]
	v_pk_fma_f32 v[90:91], v[6:7], v[34:35], v[90:91]
	v_add_f32_e32 v82, v86, v87
	v_add_f32_e32 v84, v90, v91
	v_pk_mul_f32 v[98:99], v[48:49], v[54:55] op_sel_hi:[1,0]
	v_add_f32_dpp v82, v82, v82 row_ror:8 row_mask:0xf bank_mask:0xf
	v_add_f32_dpp v84, v84, v84 row_ror:8 row_mask:0xf bank_mask:0xf
	v_add_f32_e32 v167, v92, v93
	v_add_f32_dpp v82, v82, v82 row_ror:4 row_mask:0xf bank_mask:0xf
	v_add_f32_dpp v84, v84, v84 row_ror:4 row_mask:0xf bank_mask:0xf
	v_pk_mul_f32 v[102:103], v[48:49], v[56:57] op_sel_hi:[1,0]
	v_add_f32_dpp v82, v82, v82 row_ror:2 row_mask:0xf bank_mask:0xf
	v_add_f32_dpp v84, v84, v84 row_ror:2 row_mask:0xf bank_mask:0xf
	v_add_f32_e32 v197, v94, v95
	ds_read_b128 v[136:139], v106 offset:8704
	ds_read_b128 v[140:143], v106 offset:20736
	ds_read_b128 v[144:147], v106 offset:20992
	ds_read_b128 v[148:151], v106 offset:21248
	v_pk_mul_f32 v[96:97], v[46:47], v[54:55] op_sel_hi:[1,0]
	v_pk_fma_f32 v[98:99], v[4:5], v[40:41], v[98:99]
	v_pk_mul_f32 v[100:101], v[46:47], v[56:57] op_sel_hi:[1,0]
	v_pk_fma_f32 v[102:103], v[8:9], v[40:41], v[102:103]
	ds_read_b128 v[152:155], v106 offset:8448
	v_pk_mul_f32 v[92:93], v[4:5], v[28:29]
	v_pk_mul_f32 v[94:95], v[8:9], v[28:29]
	v_add_f32_dpp v82, v82, v82 row_ror:1 row_mask:0xf bank_mask:0xf
	v_add_f32_dpp v84, v84, v84 row_ror:1 row_mask:0xf bank_mask:0xf
	ds_read_b32 v156, v107 offset:8448
	v_pk_fma_f32 v[96:97], v[2:3], v[38:39], v[96:97]
	v_pk_fma_f32 v[4:5], v[44:45], v[82:83], v[98:99] op_sel_hi:[1,0,1]
	v_pk_fma_f32 v[100:101], v[6:7], v[38:39], v[100:101]
	v_pk_fma_f32 v[8:9], v[44:45], v[84:85], v[102:103] op_sel_hi:[1,0,1]
	ds_read_b32 v158, v107 offset:8464
	v_pk_fma_f32 v[92:93], v[2:3], v[26:27], v[92:93]
	v_pk_fma_f32 v[94:95], v[6:7], v[26:27], v[94:95]
	s_waitcnt lgkmcnt(7)
	v_pk_fma_f32 v[2:3], v[42:43], v[82:83], v[96:97] op_sel_hi:[1,0,1]
	v_pk_fma_f32 v[6:7], v[42:43], v[84:85], v[100:101] op_sel_hi:[1,0,1]
	v_pk_mul_f32 v[86:87], v[4:5], v[60:61]
	v_pk_mul_f32 v[90:91], v[8:9], v[60:61]
	v_pk_fma_f32 v[86:87], v[2:3], v[58:59], v[86:87]
	v_pk_fma_f32 v[90:91], v[6:7], v[58:59], v[90:91]
	v_add_f32_e32 v82, v86, v87
	v_add_f32_e32 v84, v90, v91
	v_pk_mul_f32 v[98:99], v[72:73], v[78:79] op_sel_hi:[1,0]
	v_add_f32_dpp v82, v82, v82 row_ror:8 row_mask:0xf bank_mask:0xf
	v_add_f32_dpp v84, v84, v84 row_ror:8 row_mask:0xf bank_mask:0xf
	v_add_f32_e32 v168, v92, v93
	v_add_f32_dpp v82, v82, v82 row_ror:4 row_mask:0xf bank_mask:0xf
	v_add_f32_dpp v84, v84, v84 row_ror:4 row_mask:0xf bank_mask:0xf
	v_pk_mul_f32 v[102:103], v[72:73], v[80:81] op_sel_hi:[1,0]
	v_add_f32_dpp v82, v82, v82 row_ror:2 row_mask:0xf bank_mask:0xf
	v_add_f32_dpp v84, v84, v84 row_ror:2 row_mask:0xf bank_mask:0xf
	v_add_f32_e32 v198, v94, v95
	ds_read_b128 v[10:13], v106 offset:9472
	ds_read_b128 v[14:17], v106 offset:21504
	ds_read_b128 v[18:21], v106 offset:21760
	ds_read_b128 v[22:25], v106 offset:22016
	v_pk_mul_f32 v[96:97], v[70:71], v[78:79] op_sel_hi:[1,0]
	v_pk_fma_f32 v[98:99], v[4:5], v[64:65], v[98:99]
	v_pk_mul_f32 v[100:101], v[70:71], v[80:81] op_sel_hi:[1,0]
	v_pk_fma_f32 v[102:103], v[8:9], v[64:65], v[102:103]
	ds_read_b128 v[26:29], v106 offset:9216
	v_pk_mul_f32 v[92:93], v[4:5], v[52:53]
	v_pk_mul_f32 v[94:95], v[8:9], v[52:53]
	v_add_f32_dpp v82, v82, v82 row_ror:1 row_mask:0xf bank_mask:0xf
	v_add_f32_dpp v84, v84, v84 row_ror:1 row_mask:0xf bank_mask:0xf
	ds_read_b32 v30, v107 offset:9216
	v_pk_fma_f32 v[96:97], v[2:3], v[62:63], v[96:97]
	v_pk_fma_f32 v[4:5], v[68:69], v[82:83], v[98:99] op_sel_hi:[1,0,1]
	v_pk_fma_f32 v[100:101], v[6:7], v[62:63], v[100:101]
	v_pk_fma_f32 v[8:9], v[68:69], v[84:85], v[102:103] op_sel_hi:[1,0,1]
	ds_read_b32 v32, v107 offset:9232
	v_pk_fma_f32 v[92:93], v[2:3], v[50:51], v[92:93]
	v_pk_fma_f32 v[94:95], v[6:7], v[50:51], v[94:95]
	s_waitcnt lgkmcnt(7)
	v_pk_fma_f32 v[2:3], v[66:67], v[82:83], v[96:97] op_sel_hi:[1,0,1]
	v_pk_fma_f32 v[6:7], v[66:67], v[84:85], v[100:101] op_sel_hi:[1,0,1]
	v_pk_mul_f32 v[86:87], v[4:5], v[138:139]
	v_pk_mul_f32 v[90:91], v[8:9], v[138:139]
	v_pk_fma_f32 v[86:87], v[2:3], v[136:137], v[86:87]
	v_pk_fma_f32 v[90:91], v[6:7], v[136:137], v[90:91]
	v_add_f32_e32 v82, v86, v87
	v_add_f32_e32 v84, v90, v91
	v_pk_mul_f32 v[98:99], v[150:151], v[156:157] op_sel_hi:[1,0]
	v_add_f32_dpp v82, v82, v82 row_ror:8 row_mask:0xf bank_mask:0xf
	v_add_f32_dpp v84, v84, v84 row_ror:8 row_mask:0xf bank_mask:0xf
	v_add_f32_e32 v169, v92, v93
	v_add_f32_dpp v82, v82, v82 row_ror:4 row_mask:0xf bank_mask:0xf
	v_add_f32_dpp v84, v84, v84 row_ror:4 row_mask:0xf bank_mask:0xf
	v_pk_mul_f32 v[102:103], v[150:151], v[158:159] op_sel_hi:[1,0]
	v_add_f32_dpp v82, v82, v82 row_ror:2 row_mask:0xf bank_mask:0xf
	v_add_f32_dpp v84, v84, v84 row_ror:2 row_mask:0xf bank_mask:0xf
	v_add_f32_e32 v199, v94, v95
	ds_read_b128 v[34:37], v106 offset:10240
	ds_read_b128 v[38:41], v106 offset:22272
	ds_read_b128 v[42:45], v106 offset:22528
	ds_read_b128 v[46:49], v106 offset:22784
	v_pk_mul_f32 v[96:97], v[148:149], v[156:157] op_sel_hi:[1,0]
	v_pk_fma_f32 v[98:99], v[4:5], v[142:143], v[98:99]
	v_pk_mul_f32 v[100:101], v[148:149], v[158:159] op_sel_hi:[1,0]
	v_pk_fma_f32 v[102:103], v[8:9], v[142:143], v[102:103]
	ds_read_b128 v[50:53], v106 offset:9984
	v_pk_mul_f32 v[92:93], v[4:5], v[76:77]
	v_pk_mul_f32 v[94:95], v[8:9], v[76:77]
	v_add_f32_dpp v82, v82, v82 row_ror:1 row_mask:0xf bank_mask:0xf
	v_add_f32_dpp v84, v84, v84 row_ror:1 row_mask:0xf bank_mask:0xf
	ds_read_b32 v54, v107 offset:9984
	v_pk_fma_f32 v[96:97], v[2:3], v[140:141], v[96:97]
	v_pk_fma_f32 v[4:5], v[146:147], v[82:83], v[98:99] op_sel_hi:[1,0,1]
	v_pk_fma_f32 v[100:101], v[6:7], v[140:141], v[100:101]
	v_pk_fma_f32 v[8:9], v[146:147], v[84:85], v[102:103] op_sel_hi:[1,0,1]
	ds_read_b32 v56, v107 offset:10000
	v_pk_fma_f32 v[92:93], v[2:3], v[74:75], v[92:93]
	v_pk_fma_f32 v[94:95], v[6:7], v[74:75], v[94:95]
	s_waitcnt lgkmcnt(7)
	v_pk_fma_f32 v[2:3], v[144:145], v[82:83], v[96:97] op_sel_hi:[1,0,1]
	v_pk_fma_f32 v[6:7], v[144:145], v[84:85], v[100:101] op_sel_hi:[1,0,1]
	v_pk_mul_f32 v[86:87], v[4:5], v[12:13]
	v_pk_mul_f32 v[90:91], v[8:9], v[12:13]
	v_pk_fma_f32 v[86:87], v[2:3], v[10:11], v[86:87]
	v_pk_fma_f32 v[90:91], v[6:7], v[10:11], v[90:91]
	v_add_f32_e32 v82, v86, v87
	v_add_f32_e32 v84, v90, v91
	v_pk_mul_f32 v[98:99], v[24:25], v[30:31] op_sel_hi:[1,0]
	v_add_f32_dpp v82, v82, v82 row_ror:8 row_mask:0xf bank_mask:0xf
	v_add_f32_dpp v84, v84, v84 row_ror:8 row_mask:0xf bank_mask:0xf
	v_add_f32_e32 v170, v92, v93
	v_add_f32_dpp v82, v82, v82 row_ror:4 row_mask:0xf bank_mask:0xf
	v_add_f32_dpp v84, v84, v84 row_ror:4 row_mask:0xf bank_mask:0xf
	v_pk_mul_f32 v[102:103], v[24:25], v[32:33] op_sel_hi:[1,0]
	v_add_f32_dpp v82, v82, v82 row_ror:2 row_mask:0xf bank_mask:0xf
	v_add_f32_dpp v84, v84, v84 row_ror:2 row_mask:0xf bank_mask:0xf
	v_add_f32_e32 v200, v94, v95
	ds_read_b128 v[58:61], v106 offset:11008
	ds_read_b128 v[62:65], v106 offset:23040
	ds_read_b128 v[66:69], v106 offset:23296
	ds_read_b128 v[70:73], v106 offset:23552
	v_pk_mul_f32 v[96:97], v[22:23], v[30:31] op_sel_hi:[1,0]
	v_pk_fma_f32 v[98:99], v[4:5], v[16:17], v[98:99]
	v_pk_mul_f32 v[100:101], v[22:23], v[32:33] op_sel_hi:[1,0]
	v_pk_fma_f32 v[102:103], v[8:9], v[16:17], v[102:103]
	ds_read_b128 v[74:77], v106 offset:10752
	v_pk_mul_f32 v[92:93], v[4:5], v[154:155]
	v_pk_mul_f32 v[94:95], v[8:9], v[154:155]
	v_add_f32_dpp v82, v82, v82 row_ror:1 row_mask:0xf bank_mask:0xf
	v_add_f32_dpp v84, v84, v84 row_ror:1 row_mask:0xf bank_mask:0xf
	ds_read_b32 v78, v107 offset:10752
	v_pk_fma_f32 v[96:97], v[2:3], v[14:15], v[96:97]
	v_pk_fma_f32 v[4:5], v[20:21], v[82:83], v[98:99] op_sel_hi:[1,0,1]
	v_pk_fma_f32 v[100:101], v[6:7], v[14:15], v[100:101]
	v_pk_fma_f32 v[8:9], v[20:21], v[84:85], v[102:103] op_sel_hi:[1,0,1]
	ds_read_b32 v80, v107 offset:10768
	v_pk_fma_f32 v[92:93], v[2:3], v[152:153], v[92:93]
	v_pk_fma_f32 v[94:95], v[6:7], v[152:153], v[94:95]
	s_waitcnt lgkmcnt(7)
	v_pk_fma_f32 v[2:3], v[18:19], v[82:83], v[96:97] op_sel_hi:[1,0,1]
	v_pk_fma_f32 v[6:7], v[18:19], v[84:85], v[100:101] op_sel_hi:[1,0,1]
	v_pk_mul_f32 v[86:87], v[4:5], v[36:37]
	v_pk_mul_f32 v[90:91], v[8:9], v[36:37]
	v_pk_fma_f32 v[86:87], v[2:3], v[34:35], v[86:87]
	v_pk_fma_f32 v[90:91], v[6:7], v[34:35], v[90:91]
	v_add_f32_e32 v82, v86, v87
	v_add_f32_e32 v84, v90, v91
	v_pk_mul_f32 v[98:99], v[48:49], v[54:55] op_sel_hi:[1,0]
	v_add_f32_dpp v82, v82, v82 row_ror:8 row_mask:0xf bank_mask:0xf
	v_add_f32_dpp v84, v84, v84 row_ror:8 row_mask:0xf bank_mask:0xf
	v_add_f32_e32 v171, v92, v93
	v_add_f32_dpp v82, v82, v82 row_ror:4 row_mask:0xf bank_mask:0xf
	v_add_f32_dpp v84, v84, v84 row_ror:4 row_mask:0xf bank_mask:0xf
	v_pk_mul_f32 v[102:103], v[48:49], v[56:57] op_sel_hi:[1,0]
	v_add_f32_dpp v82, v82, v82 row_ror:2 row_mask:0xf bank_mask:0xf
	v_add_f32_dpp v84, v84, v84 row_ror:2 row_mask:0xf bank_mask:0xf
	v_add_f32_e32 v201, v94, v95
	ds_read_b128 v[136:139], v106 offset:11776
	ds_read_b128 v[140:143], v106 offset:23808
	ds_read_b128 v[144:147], v106 offset:24064
	ds_read_b128 v[148:151], v106 offset:24320
	v_pk_mul_f32 v[96:97], v[46:47], v[54:55] op_sel_hi:[1,0]
	v_pk_fma_f32 v[98:99], v[4:5], v[40:41], v[98:99]
	v_pk_mul_f32 v[100:101], v[46:47], v[56:57] op_sel_hi:[1,0]
	v_pk_fma_f32 v[102:103], v[8:9], v[40:41], v[102:103]
	ds_read_b128 v[152:155], v106 offset:11520
	v_pk_mul_f32 v[92:93], v[4:5], v[28:29]
	v_pk_mul_f32 v[94:95], v[8:9], v[28:29]
	v_add_f32_dpp v82, v82, v82 row_ror:1 row_mask:0xf bank_mask:0xf
	v_add_f32_dpp v84, v84, v84 row_ror:1 row_mask:0xf bank_mask:0xf
	ds_read_b32 v156, v107 offset:11520
	v_pk_fma_f32 v[96:97], v[2:3], v[38:39], v[96:97]
	v_pk_fma_f32 v[4:5], v[44:45], v[82:83], v[98:99] op_sel_hi:[1,0,1]
	v_pk_fma_f32 v[100:101], v[6:7], v[38:39], v[100:101]
	v_pk_fma_f32 v[8:9], v[44:45], v[84:85], v[102:103] op_sel_hi:[1,0,1]
	ds_read_b32 v158, v107 offset:11536
	v_pk_fma_f32 v[92:93], v[2:3], v[26:27], v[92:93]
	v_pk_fma_f32 v[94:95], v[6:7], v[26:27], v[94:95]
	s_waitcnt lgkmcnt(7)
	v_pk_fma_f32 v[2:3], v[42:43], v[82:83], v[96:97] op_sel_hi:[1,0,1]
	v_pk_fma_f32 v[6:7], v[42:43], v[84:85], v[100:101] op_sel_hi:[1,0,1]
	v_pk_mul_f32 v[86:87], v[4:5], v[60:61]
	v_pk_mul_f32 v[90:91], v[8:9], v[60:61]
	v_pk_fma_f32 v[86:87], v[2:3], v[58:59], v[86:87]
	v_pk_fma_f32 v[90:91], v[6:7], v[58:59], v[90:91]
	v_add_f32_e32 v82, v86, v87
	v_add_f32_e32 v84, v90, v91
	v_pk_mul_f32 v[98:99], v[72:73], v[78:79] op_sel_hi:[1,0]
	v_add_f32_dpp v82, v82, v82 row_ror:8 row_mask:0xf bank_mask:0xf
	v_add_f32_dpp v84, v84, v84 row_ror:8 row_mask:0xf bank_mask:0xf
	v_add_f32_e32 v172, v92, v93
	v_add_f32_dpp v82, v82, v82 row_ror:4 row_mask:0xf bank_mask:0xf
	v_add_f32_dpp v84, v84, v84 row_ror:4 row_mask:0xf bank_mask:0xf
	v_pk_mul_f32 v[102:103], v[72:73], v[80:81] op_sel_hi:[1,0]
	v_add_f32_dpp v82, v82, v82 row_ror:2 row_mask:0xf bank_mask:0xf
	v_add_f32_dpp v84, v84, v84 row_ror:2 row_mask:0xf bank_mask:0xf
	v_add_f32_e32 v202, v94, v95
	ds_read_b128 v[10:13], v108 offset:256
	ds_read_b128 v[14:17], v108 offset:12288
	ds_read_b128 v[18:21], v108 offset:12544
	ds_read_b128 v[22:25], v108 offset:12800
	v_pk_mul_f32 v[96:97], v[70:71], v[78:79] op_sel_hi:[1,0]
	v_pk_fma_f32 v[98:99], v[4:5], v[64:65], v[98:99]
	v_pk_mul_f32 v[100:101], v[70:71], v[80:81] op_sel_hi:[1,0]
	v_pk_fma_f32 v[102:103], v[8:9], v[64:65], v[102:103]
	ds_read_b128 v[26:29], v108 offset:0
	v_pk_mul_f32 v[92:93], v[4:5], v[52:53]
	v_pk_mul_f32 v[94:95], v[8:9], v[52:53]
	v_add_f32_dpp v82, v82, v82 row_ror:1 row_mask:0xf bank_mask:0xf
	v_add_f32_dpp v84, v84, v84 row_ror:1 row_mask:0xf bank_mask:0xf
	ds_read_b32 v30, v109 offset:0
	v_pk_fma_f32 v[96:97], v[2:3], v[62:63], v[96:97]
	v_pk_fma_f32 v[4:5], v[68:69], v[82:83], v[98:99] op_sel_hi:[1,0,1]
	v_pk_fma_f32 v[100:101], v[6:7], v[62:63], v[100:101]
	v_pk_fma_f32 v[8:9], v[68:69], v[84:85], v[102:103] op_sel_hi:[1,0,1]
	ds_read_b32 v32, v109 offset:16
	v_pk_fma_f32 v[92:93], v[2:3], v[50:51], v[92:93]
	v_pk_fma_f32 v[94:95], v[6:7], v[50:51], v[94:95]
	s_waitcnt lgkmcnt(7)
	v_pk_fma_f32 v[2:3], v[66:67], v[82:83], v[96:97] op_sel_hi:[1,0,1]
	v_pk_fma_f32 v[6:7], v[66:67], v[84:85], v[100:101] op_sel_hi:[1,0,1]
	v_pk_mul_f32 v[86:87], v[4:5], v[138:139]
	v_pk_mul_f32 v[90:91], v[8:9], v[138:139]
	v_pk_fma_f32 v[86:87], v[2:3], v[136:137], v[86:87]
	v_pk_fma_f32 v[90:91], v[6:7], v[136:137], v[90:91]
	v_add_f32_e32 v82, v86, v87
	v_add_f32_e32 v84, v90, v91
	v_add_f32_e32 v173, v92, v93
	v_add_f32_dpp v82, v82, v82 row_ror:8 row_mask:0xf bank_mask:0xf
	v_add_f32_dpp v84, v84, v84 row_ror:8 row_mask:0xf bank_mask:0xf
	v_add_f32_e32 v203, v94, v95
	v_add_f32_dpp v82, v82, v82 row_ror:4 row_mask:0xf bank_mask:0xf
	v_add_f32_dpp v84, v84, v84 row_ror:4 row_mask:0xf bank_mask:0xf
	v_pk_mul_f32 v[98:99], v[150:151], v[156:157] op_sel_hi:[1,0]
	v_add_f32_dpp v82, v82, v82 row_ror:2 row_mask:0xf bank_mask:0xf
	v_add_f32_dpp v84, v84, v84 row_ror:2 row_mask:0xf bank_mask:0xf
	v_pk_mul_f32 v[102:103], v[150:151], v[158:159] op_sel_hi:[1,0]
	v_pk_mul_f32 v[92:93], v[4:5], v[76:77]
	v_pk_mul_f32 v[94:95], v[8:9], v[76:77]
	v_pk_mul_f32 v[96:97], v[148:149], v[156:157] op_sel_hi:[1,0]
	v_pk_fma_f32 v[98:99], v[4:5], v[142:143], v[98:99]
	v_pk_mul_f32 v[100:101], v[148:149], v[158:159] op_sel_hi:[1,0]
	v_pk_fma_f32 v[102:103], v[8:9], v[142:143], v[102:103]
	v_pk_fma_f32 v[92:93], v[2:3], v[74:75], v[92:93]
	v_pk_fma_f32 v[94:95], v[6:7], v[74:75], v[94:95]
	v_add_f32_dpp v82, v82, v82 row_ror:1 row_mask:0xf bank_mask:0xf
	v_add_f32_dpp v84, v84, v84 row_ror:1 row_mask:0xf bank_mask:0xf
	v_pk_fma_f32 v[96:97], v[2:3], v[140:141], v[96:97]
	v_pk_fma_f32 v[4:5], v[146:147], v[82:83], v[98:99] op_sel_hi:[1,0,1]
	v_pk_fma_f32 v[100:101], v[6:7], v[140:141], v[100:101]
	v_pk_fma_f32 v[8:9], v[146:147], v[84:85], v[102:103] op_sel_hi:[1,0,1]
	v_add_f32_e32 v174, v92, v93
	v_add_f32_e32 v204, v94, v95
	v_pk_fma_f32 v[2:3], v[144:145], v[82:83], v[96:97] op_sel_hi:[1,0,1]
	v_pk_fma_f32 v[6:7], v[144:145], v[84:85], v[100:101] op_sel_hi:[1,0,1]
	v_pk_mul_f32 v[92:93], v[4:5], v[154:155]
	v_pk_mul_f32 v[94:95], v[8:9], v[154:155]
	v_pk_fma_f32 v[92:93], v[2:3], v[152:153], v[92:93]
	v_pk_fma_f32 v[94:95], v[6:7], v[152:153], v[94:95]
	v_add_f32_e32 v175, v92, v93
	v_add_f32_e32 v205, v94, v95
	v_add_f32_dpp v160, v160, v160 row_mirror row_mask:0xf bank_mask:0x3
	v_add_f32_dpp v161, v161, v161 row_mirror row_mask:0xf bank_mask:0x3
	v_add_f32_dpp v162, v162, v162 row_mirror row_mask:0xf bank_mask:0x3
	v_add_f32_dpp v163, v163, v163 row_mirror row_mask:0xf bank_mask:0x3
	v_add_f32_dpp v190, v190, v190 row_mirror row_mask:0xf bank_mask:0x3
	v_add_f32_dpp v191, v191, v191 row_mirror row_mask:0xf bank_mask:0x3
	v_add_f32_dpp v192, v192, v192 row_mirror row_mask:0xf bank_mask:0x3
	v_add_f32_dpp v193, v193, v193 row_mirror row_mask:0xf bank_mask:0x3
	v_add_f32_dpp v160, v168, v168 row_mirror row_mask:0xf bank_mask:0xc
	v_add_f32_dpp v161, v169, v169 row_mirror row_mask:0xf bank_mask:0xc
	v_add_f32_dpp v162, v170, v170 row_mirror row_mask:0xf bank_mask:0xc
	v_add_f32_dpp v163, v171, v171 row_mirror row_mask:0xf bank_mask:0xc
	v_add_f32_dpp v164, v164, v164 row_mirror row_mask:0xf bank_mask:0x3
	v_add_f32_dpp v165, v165, v165 row_mirror row_mask:0xf bank_mask:0x3
	v_add_f32_dpp v166, v166, v166 row_mirror row_mask:0xf bank_mask:0x3
	v_add_f32_dpp v167, v167, v167 row_mirror row_mask:0xf bank_mask:0x3
	v_add_f32_dpp v190, v198, v198 row_mirror row_mask:0xf bank_mask:0xc
	v_add_f32_dpp v191, v199, v199 row_mirror row_mask:0xf bank_mask:0xc
	v_add_f32_dpp v192, v200, v200 row_mirror row_mask:0xf bank_mask:0xc
	v_add_f32_dpp v193, v201, v201 row_mirror row_mask:0xf bank_mask:0xc
	v_add_f32_dpp v194, v194, v194 row_mirror row_mask:0xf bank_mask:0x3
	v_add_f32_dpp v195, v195, v195 row_mirror row_mask:0xf bank_mask:0x3
	v_add_f32_dpp v196, v196, v196 row_mirror row_mask:0xf bank_mask:0x3
	v_add_f32_dpp v197, v197, v197 row_mirror row_mask:0xf bank_mask:0x3
	v_add_f32_dpp v164, v172, v172 row_mirror row_mask:0xf bank_mask:0xc
	v_add_f32_dpp v165, v173, v173 row_mirror row_mask:0xf bank_mask:0xc
	v_add_f32_dpp v166, v174, v174 row_mirror row_mask:0xf bank_mask:0xc
	v_add_f32_dpp v167, v175, v175 row_mirror row_mask:0xf bank_mask:0xc
	v_add_f32_dpp v194, v202, v202 row_mirror row_mask:0xf bank_mask:0xc
	v_add_f32_dpp v195, v203, v203 row_mirror row_mask:0xf bank_mask:0xc
	v_add_f32_dpp v196, v204, v204 row_mirror row_mask:0xf bank_mask:0xc
	v_add_f32_dpp v197, v205, v205 row_mirror row_mask:0xf bank_mask:0xc
	v_add_f32_dpp v160, v160, v160 row_half_mirror row_mask:0xf bank_mask:0x5
	v_add_f32_dpp v161, v161, v161 row_half_mirror row_mask:0xf bank_mask:0x5
	v_add_f32_dpp v162, v162, v162 row_half_mirror row_mask:0xf bank_mask:0x5
	v_add_f32_dpp v163, v163, v163 row_half_mirror row_mask:0xf bank_mask:0x5
	v_add_f32_dpp v190, v190, v190 row_half_mirror row_mask:0xf bank_mask:0x5
	v_add_f32_dpp v191, v191, v191 row_half_mirror row_mask:0xf bank_mask:0x5
	v_add_f32_dpp v160, v164, v164 row_half_mirror row_mask:0xf bank_mask:0xa
	v_add_f32_dpp v161, v165, v165 row_half_mirror row_mask:0xf bank_mask:0xa
	v_add_f32_dpp v162, v166, v166 row_half_mirror row_mask:0xf bank_mask:0xa
	v_add_f32_dpp v163, v167, v167 row_half_mirror row_mask:0xf bank_mask:0xa
	v_add_f32_dpp v190, v194, v194 row_half_mirror row_mask:0xf bank_mask:0xa
	v_cndmask_b32_e64 v169, v162, v160, s[10:11]
	v_cndmask_b32_e64 v171, v163, v161, s[10:11]
	ds_read_b128 v[34:37], v108 offset:1024
	v_add_f32_dpp v191, v195, v195 row_half_mirror row_mask:0xf bank_mask:0xa
	ds_read_b128 v[38:41], v108 offset:13056
	v_add_f32_dpp v192, v192, v192 row_half_mirror row_mask:0xf bank_mask:0x5
	v_cndmask_b32_e64 v168, v160, v162, s[10:11]
	v_cndmask_b32_e64 v170, v161, v163, s[10:11]
	ds_read_b128 v[42:45], v108 offset:13312
	v_add_f32_dpp v192, v196, v196 row_half_mirror row_mask:0xf bank_mask:0xa
	v_add_f32_dpp v168, v169, v168 quad_perm:[2,3,0,1] row_mask:0xf bank_mask:0xf
	v_add_f32_dpp v170, v171, v170 quad_perm:[2,3,0,1] row_mask:0xf bank_mask:0xf
	ds_read_b128 v[46:49], v108 offset:13568
	v_add_f32_dpp v193, v193, v193 row_half_mirror row_mask:0xf bank_mask:0x5
	v_cndmask_b32_e64 v169, v170, v168, s[14:15]
	ds_read_b128 v[50:53], v108 offset:768
	v_add_f32_dpp v193, v197, v197 row_half_mirror row_mask:0xf bank_mask:0xa
	ds_read_b32 v54, v109 offset:768
	v_cndmask_b32_e64 v198, v190, v192, s[10:11]
	v_cndmask_b32_e64 v171, v168, v170, s[14:15]
	ds_read_b32 v56, v109 offset:784
	v_cndmask_b32_e64 v199, v192, v190, s[10:11]
	v_cndmask_b32_e64 v201, v193, v191, s[10:11]
	v_cndmask_b32_e64 v200, v191, v193, s[10:11]
	v_add_f32_dpp v198, v199, v198 quad_perm:[2,3,0,1] row_mask:0xf bank_mask:0xf
	v_add_f32_dpp v200, v201, v200 quad_perm:[2,3,0,1] row_mask:0xf bank_mask:0xf
	v_cndmask_b32_e64 v199, v200, v198, s[14:15]
	v_cndmask_b32_e64 v201, v198, v200, s[14:15]
	v_add_f32_dpp v171, v169, v171 quad_perm:[1,0,3,2] row_mask:0xf bank_mask:0xf
	v_add_f32_dpp v201, v199, v201 quad_perm:[1,0,3,2] row_mask:0xf bank_mask:0xf
	s_mov_b32 s8, s20
	v_mov_b32_e32 v106, v108
	v_mov_b32_e32 v107, v109
	global_store_dword v113, v171, s[4:5]
	global_store_dword v113, v201, s[4:5] offset:16
	s_add_u32 s4, s4, s6
	s_addc_u32 s5, s5, s7
	s_sub_u32 s1, s1, 1
	s_cmp_lg_u32 s1, 0
	s_cbranch_scc1 .Lsc_c_loop_pb
	s_cmp_lt_u32 s71, 64
	s_cbranch_scc1 .Lsc_c_end_pb
	v_readlane_b32 s4, v253, 49
	v_readlane_b32 s5, v253, 50
	s_nop 3
	s_add_u32 s4, s4, s9
	s_addc_u32 s5, s5, 0
	s_nop 3
	global_store_dwordx4 v114, v[2:5], s[4:5]
	global_store_dwordx4 v114, v[6:9], s[4:5] offset:1024
.Lsc_c_end_pb:
	s_waitcnt lgkmcnt(0)
	s_waitcnt vmcnt(0)
	s_barrier
